# NSA top-13 selection: candidate range split evenly over the four lane groups, insertion trips ceil((ncand+1)/16) instead of 16
# baseline (speedup 1.0000x reference)
; DI void nsa_item(const Params& p, int bk, int qb, char* smem, float Mb) {
;     ...
;             if (ncand > need) {
;                 float key[4][4];
; #pragma unroll
;                 for (int u = 0; u < 4; ++u)
; #pragma unroll
;                     for (int r = 0; r < 4; ++r) {
;                         const int j = lane + 64 * r;
;                         key[u][r] = (j >= 1 && j <= cur - 2) ? imp[(qi + u) * 260 + j] : -1.f;
;                     }
;                 for (int s = 0; s < need; ++s) {
; #pragma unroll
;                     for (int u = 0; u < 4; ++u) {
;                         const float best = wave_max(fmaxf(fmaxf(key[u][0], key[u][1]), fmaxf(key[u][2], key[u][3])));
;                         int jstar = 1 << 20;
; #pragma unroll
;                         for (int r = 3; r >= 0; --r) {
;                             const unsigned long long bm = __ballot(key[u][r] == best);
;                             if (bm) jstar = 64 * r + (int)__builtin_ctzll(bm);
;                         }
; #pragma unroll
;                         for (int r = 0; r < 4; ++r) if (lane + 64 * r == jstar) key[u][r] = -1.f;
;                         if (lane == 0) sel[(qi + u) * 16 + nforced + s] = jstar;
;                     }
;                 }
.LBB0_524:
	s_and_b64 s[24:25], s[4:5], exec
	s_cbranch_scc0 .Ltopk_skip
	s_mov_b64 s[20:21], vcc
	s_mov_b64 s[22:23], exec
	v_and_b32_e32 v28, 15, v146
	v_lshrrev_b32_e32 v29, 4, v146
	v_add_u32_e32 v32, -2, v238
	v_add_u32_e32 v8, 16, v32
	v_lshrrev_b32_e32 v8, 4, v8
	v_mul_u32_u24_e32 v30, 0x410, v28
	v_readfirstlane_b32 s24, v8
	v_lshlrev_b32_e32 v8, 2, v8
	v_mul_u32_u24_e32 v31, v29, v8
	v_add_u32_e32 v30, s90, v30
	v_lshl_add_u32 v30, v31, 2, v30
	v_mov_b32_e32 v33, -1.0
	v_mov_b32_e32 v34, -1.0
	v_mov_b32_e32 v35, -1.0
	v_mov_b32_e32 v36, -1.0
	v_mov_b32_e32 v37, -1.0
	v_mov_b32_e32 v38, -1.0
	v_mov_b32_e32 v39, -1.0
	v_mov_b32_e32 v40, -1.0
	v_mov_b32_e32 v41, -1.0
	v_mov_b32_e32 v42, -1.0
	v_mov_b32_e32 v43, -1.0
	v_mov_b32_e32 v44, -1.0
	v_mov_b32_e32 v45, -1.0
	v_mov_b32_e32 v46, 0
	v_mov_b32_e32 v47, 0
	v_mov_b32_e32 v48, 0
	v_mov_b32_e32 v49, 0
	v_mov_b32_e32 v50, 0
	v_mov_b32_e32 v51, 0
	v_mov_b32_e32 v52, 0
	v_mov_b32_e32 v53, 0
	v_mov_b32_e32 v54, 0
	v_mov_b32_e32 v55, 0
	v_mov_b32_e32 v56, 0
	v_mov_b32_e32 v57, 0
	v_mov_b32_e32 v58, 0
	s_mov_b32 s26, 0
.Ltopk_loop:
	ds_read_b128 v[8:11], v30
	v_add_u32_e32 v30, 16, v30
	s_waitcnt lgkmcnt(0)
	v_add_u32_e32 v13, -1, v31
	v_cmp_gt_u32_e64 s[18:19], v32, v13
	v_mov_b32_e32 v13, v31
	s_nop 0
	v_cndmask_b32_e64 v12, -1.0, v8, s[18:19]
	v_cmp_gt_f32_e64 vcc, v12, v33
	s_nop 1
	v_cndmask_b32_e64 v14, v12, v33, vcc
	v_cmp_gt_f32_e64 s[14:15], v14, v34
	v_cndmask_b32_e64 v33, v33, v12, vcc
	v_cndmask_b32_e64 v15, v13, v46, vcc
	v_cndmask_b32_e64 v46, v46, v13, vcc
	v_cndmask_b32_e64 v12, v14, v34, s[14:15]
	v_cmp_gt_f32_e64 vcc, v12, v35
	v_cndmask_b32_e64 v34, v34, v14, s[14:15]
	v_cndmask_b32_e64 v13, v15, v47, s[14:15]
	v_cndmask_b32_e64 v47, v47, v15, s[14:15]
	v_cndmask_b32_e64 v14, v12, v35, vcc
	v_cmp_gt_f32_e64 s[14:15], v14, v36
	v_cndmask_b32_e64 v35, v35, v12, vcc
	v_cndmask_b32_e64 v15, v13, v48, vcc
	v_cndmask_b32_e64 v48, v48, v13, vcc
	v_cndmask_b32_e64 v12, v14, v36, s[14:15]
	v_cmp_gt_f32_e64 vcc, v12, v37
	v_cndmask_b32_e64 v36, v36, v14, s[14:15]
	v_cndmask_b32_e64 v13, v15, v49, s[14:15]
	v_cndmask_b32_e64 v49, v49, v15, s[14:15]
	v_cndmask_b32_e64 v14, v12, v37, vcc
	v_cmp_gt_f32_e64 s[14:15], v14, v38
	v_cndmask_b32_e64 v37, v37, v12, vcc
	v_cndmask_b32_e64 v15, v13, v50, vcc
	v_cndmask_b32_e64 v50, v50, v13, vcc
	v_cndmask_b32_e64 v12, v14, v38, s[14:15]
	v_cmp_gt_f32_e64 vcc, v12, v39
	v_cndmask_b32_e64 v38, v38, v14, s[14:15]
	v_cndmask_b32_e64 v13, v15, v51, s[14:15]
	v_cndmask_b32_e64 v51, v51, v15, s[14:15]
	v_cndmask_b32_e64 v14, v12, v39, vcc
	v_cmp_gt_f32_e64 s[14:15], v14, v40
	v_cndmask_b32_e64 v39, v39, v12, vcc
	v_cndmask_b32_e64 v15, v13, v52, vcc
	v_cndmask_b32_e64 v52, v52, v13, vcc
	v_cndmask_b32_e64 v12, v14, v40, s[14:15]
	v_cmp_gt_f32_e64 vcc, v12, v41
	v_cndmask_b32_e64 v40, v40, v14, s[14:15]
	v_cndmask_b32_e64 v13, v15, v53, s[14:15]
	v_cndmask_b32_e64 v53, v53, v15, s[14:15]
	v_cndmask_b32_e64 v14, v12, v41, vcc
	v_cmp_gt_f32_e64 s[14:15], v14, v42
	v_cndmask_b32_e64 v41, v41, v12, vcc
	v_cndmask_b32_e64 v15, v13, v54, vcc
	v_cndmask_b32_e64 v54, v54, v13, vcc
	v_cndmask_b32_e64 v12, v14, v42, s[14:15]
	v_cmp_gt_f32_e64 vcc, v12, v43
	v_cndmask_b32_e64 v42, v42, v14, s[14:15]
	v_cndmask_b32_e64 v13, v15, v55, s[14:15]
	v_cndmask_b32_e64 v55, v55, v15, s[14:15]
	v_cndmask_b32_e64 v14, v12, v43, vcc
	v_cmp_gt_f32_e64 s[14:15], v14, v44
	v_cndmask_b32_e64 v43, v43, v12, vcc
	v_cndmask_b32_e64 v15, v13, v56, vcc
	v_cndmask_b32_e64 v56, v56, v13, vcc
	v_cndmask_b32_e64 v12, v14, v44, s[14:15]
	v_cmp_gt_f32_e64 vcc, v12, v45
	v_cndmask_b32_e64 v44, v44, v14, s[14:15]
	v_cndmask_b32_e64 v13, v15, v57, s[14:15]
	v_cndmask_b32_e64 v57, v57, v15, s[14:15]
	v_cndmask_b32_e64 v14, v12, v45, vcc
	s_nop 0
	v_cndmask_b32_e64 v45, v45, v12, vcc
	v_cndmask_b32_e64 v58, v58, v13, vcc
	v_mov_b32_e32 v13, v31
	v_cmp_gt_u32_e64 s[18:19], v32, v13
	v_add_u32_e32 v13, 1, v31
	s_nop 0
	v_cndmask_b32_e64 v12, -1.0, v9, s[18:19]
	v_cmp_gt_f32_e64 vcc, v12, v33
	s_nop 1
	v_cndmask_b32_e64 v14, v12, v33, vcc
	v_cmp_gt_f32_e64 s[14:15], v14, v34
	v_cndmask_b32_e64 v33, v33, v12, vcc
	v_cndmask_b32_e64 v15, v13, v46, vcc
	v_cndmask_b32_e64 v46, v46, v13, vcc
	v_cndmask_b32_e64 v12, v14, v34, s[14:15]
	v_cmp_gt_f32_e64 vcc, v12, v35
	v_cndmask_b32_e64 v34, v34, v14, s[14:15]
	v_cndmask_b32_e64 v13, v15, v47, s[14:15]
	v_cndmask_b32_e64 v47, v47, v15, s[14:15]
	v_cndmask_b32_e64 v14, v12, v35, vcc
	v_cmp_gt_f32_e64 s[14:15], v14, v36
	v_cndmask_b32_e64 v35, v35, v12, vcc
	v_cndmask_b32_e64 v15, v13, v48, vcc
	v_cndmask_b32_e64 v48, v48, v13, vcc
	v_cndmask_b32_e64 v12, v14, v36, s[14:15]
	v_cmp_gt_f32_e64 vcc, v12, v37
	v_cndmask_b32_e64 v36, v36, v14, s[14:15]
	v_cndmask_b32_e64 v13, v15, v49, s[14:15]
	v_cndmask_b32_e64 v49, v49, v15, s[14:15]
	v_cndmask_b32_e64 v14, v12, v37, vcc
	v_cmp_gt_f32_e64 s[14:15], v14, v38
	v_cndmask_b32_e64 v37, v37, v12, vcc
	v_cndmask_b32_e64 v15, v13, v50, vcc
	v_cndmask_b32_e64 v50, v50, v13, vcc
	v_cndmask_b32_e64 v12, v14, v38, s[14:15]
	v_cmp_gt_f32_e64 vcc, v12, v39
	v_cndmask_b32_e64 v38, v38, v14, s[14:15]
	v_cndmask_b32_e64 v13, v15, v51, s[14:15]
	v_cndmask_b32_e64 v51, v51, v15, s[14:15]
	v_cndmask_b32_e64 v14, v12, v39, vcc
	v_cmp_gt_f32_e64 s[14:15], v14, v40
	v_cndmask_b32_e64 v39, v39, v12, vcc
	v_cndmask_b32_e64 v15, v13, v52, vcc
	v_cndmask_b32_e64 v52, v52, v13, vcc
	v_cndmask_b32_e64 v12, v14, v40, s[14:15]
	v_cmp_gt_f32_e64 vcc, v12, v41
	v_cndmask_b32_e64 v40, v40, v14, s[14:15]
	v_cndmask_b32_e64 v13, v15, v53, s[14:15]
	v_cndmask_b32_e64 v53, v53, v15, s[14:15]
	v_cndmask_b32_e64 v14, v12, v41, vcc
; DI void nsa_item(const Params& p, int bk, int qb, char* smem, float Mb) {
;     ...
;             if (ncand > need) {
;                 float key[4][4];
; #pragma unroll
;                 for (int u = 0; u < 4; ++u)
; #pragma unroll
;                     for (int r = 0; r < 4; ++r) {
;                         const int j = lane + 64 * r;
;                         key[u][r] = (j >= 1 && j <= cur - 2) ? imp[(qi + u) * 260 + j] : -1.f;
;                     }
;                 for (int s = 0; s < need; ++s) {
; #pragma unroll
;                     for (int u = 0; u < 4; ++u) {
;                         const float best = wave_max(fmaxf(fmaxf(key[u][0], key[u][1]), fmaxf(key[u][2], key[u][3])));
;                         int jstar = 1 << 20;
; #pragma unroll
;                         for (int r = 3; r >= 0; --r) {
;                             const unsigned long long bm = __ballot(key[u][r] == best);
;                             if (bm) jstar = 64 * r + (int)__builtin_ctzll(bm);
;                         }
; #pragma unroll
;                         for (int r = 0; r < 4; ++r) if (lane + 64 * r == jstar) key[u][r] = -1.f;
;                         if (lane == 0) sel[(qi + u) * 16 + nforced + s] = jstar;
;                     }
;                 }
	v_cmp_gt_f32_e64 s[14:15], v14, v42
	v_cndmask_b32_e64 v41, v41, v12, vcc
	v_cndmask_b32_e64 v15, v13, v54, vcc
	v_cndmask_b32_e64 v54, v54, v13, vcc
	v_cndmask_b32_e64 v12, v14, v42, s[14:15]
	v_cmp_gt_f32_e64 vcc, v12, v43
	v_cndmask_b32_e64 v42, v42, v14, s[14:15]
	v_cndmask_b32_e64 v13, v15, v55, s[14:15]
	v_cndmask_b32_e64 v55, v55, v15, s[14:15]
	v_cndmask_b32_e64 v14, v12, v43, vcc
	v_cmp_gt_f32_e64 s[14:15], v14, v44
	v_cndmask_b32_e64 v43, v43, v12, vcc
	v_cndmask_b32_e64 v15, v13, v56, vcc
	v_cndmask_b32_e64 v56, v56, v13, vcc
	v_cndmask_b32_e64 v12, v14, v44, s[14:15]
	v_cmp_gt_f32_e64 vcc, v12, v45
	v_cndmask_b32_e64 v44, v44, v14, s[14:15]
	v_cndmask_b32_e64 v13, v15, v57, s[14:15]
	v_cndmask_b32_e64 v57, v57, v15, s[14:15]
	v_cndmask_b32_e64 v14, v12, v45, vcc
	s_nop 0
	v_cndmask_b32_e64 v45, v45, v12, vcc
	v_cndmask_b32_e64 v58, v58, v13, vcc
	v_add_u32_e32 v13, 1, v31
	v_cmp_gt_u32_e64 s[18:19], v32, v13
	v_add_u32_e32 v13, 2, v31
	s_nop 0
	v_cndmask_b32_e64 v12, -1.0, v10, s[18:19]
	v_cmp_gt_f32_e64 vcc, v12, v33
	s_nop 1
	v_cndmask_b32_e64 v14, v12, v33, vcc
	v_cmp_gt_f32_e64 s[14:15], v14, v34
	v_cndmask_b32_e64 v33, v33, v12, vcc
	v_cndmask_b32_e64 v15, v13, v46, vcc
	v_cndmask_b32_e64 v46, v46, v13, vcc
	v_cndmask_b32_e64 v12, v14, v34, s[14:15]
	v_cmp_gt_f32_e64 vcc, v12, v35
	v_cndmask_b32_e64 v34, v34, v14, s[14:15]
	v_cndmask_b32_e64 v13, v15, v47, s[14:15]
	v_cndmask_b32_e64 v47, v47, v15, s[14:15]
	v_cndmask_b32_e64 v14, v12, v35, vcc
	v_cmp_gt_f32_e64 s[14:15], v14, v36
	v_cndmask_b32_e64 v35, v35, v12, vcc
	v_cndmask_b32_e64 v15, v13, v48, vcc
	v_cndmask_b32_e64 v48, v48, v13, vcc
	v_cndmask_b32_e64 v12, v14, v36, s[14:15]
	v_cmp_gt_f32_e64 vcc, v12, v37
	v_cndmask_b32_e64 v36, v36, v14, s[14:15]
	v_cndmask_b32_e64 v13, v15, v49, s[14:15]
	v_cndmask_b32_e64 v49, v49, v15, s[14:15]
	v_cndmask_b32_e64 v14, v12, v37, vcc
	v_cmp_gt_f32_e64 s[14:15], v14, v38
	v_cndmask_b32_e64 v37, v37, v12, vcc
	v_cndmask_b32_e64 v15, v13, v50, vcc
	v_cndmask_b32_e64 v50, v50, v13, vcc
	v_cndmask_b32_e64 v12, v14, v38, s[14:15]
	v_cmp_gt_f32_e64 vcc, v12, v39
	v_cndmask_b32_e64 v38, v38, v14, s[14:15]
	v_cndmask_b32_e64 v13, v15, v51, s[14:15]
	v_cndmask_b32_e64 v51, v51, v15, s[14:15]
	v_cndmask_b32_e64 v14, v12, v39, vcc
	v_cmp_gt_f32_e64 s[14:15], v14, v40
	v_cndmask_b32_e64 v39, v39, v12, vcc
	v_cndmask_b32_e64 v15, v13, v52, vcc
	v_cndmask_b32_e64 v52, v52, v13, vcc
	v_cndmask_b32_e64 v12, v14, v40, s[14:15]
	v_cmp_gt_f32_e64 vcc, v12, v41
	v_cndmask_b32_e64 v40, v40, v14, s[14:15]
	v_cndmask_b32_e64 v13, v15, v53, s[14:15]
	v_cndmask_b32_e64 v53, v53, v15, s[14:15]
	v_cndmask_b32_e64 v14, v12, v41, vcc
	v_cmp_gt_f32_e64 s[14:15], v14, v42
	v_cndmask_b32_e64 v41, v41, v12, vcc
	v_cndmask_b32_e64 v15, v13, v54, vcc
	v_cndmask_b32_e64 v54, v54, v13, vcc
	v_cndmask_b32_e64 v12, v14, v42, s[14:15]
	v_cmp_gt_f32_e64 vcc, v12, v43
	v_cndmask_b32_e64 v42, v42, v14, s[14:15]
	v_cndmask_b32_e64 v13, v15, v55, s[14:15]
	v_cndmask_b32_e64 v55, v55, v15, s[14:15]
	v_cndmask_b32_e64 v14, v12, v43, vcc
	v_cmp_gt_f32_e64 s[14:15], v14, v44
	v_cndmask_b32_e64 v43, v43, v12, vcc
	v_cndmask_b32_e64 v15, v13, v56, vcc
	v_cndmask_b32_e64 v56, v56, v13, vcc
	v_cndmask_b32_e64 v12, v14, v44, s[14:15]
	v_cmp_gt_f32_e64 vcc, v12, v45
	v_cndmask_b32_e64 v44, v44, v14, s[14:15]
	v_cndmask_b32_e64 v13, v15, v57, s[14:15]
	v_cndmask_b32_e64 v57, v57, v15, s[14:15]
	v_cndmask_b32_e64 v14, v12, v45, vcc
	s_nop 0
	v_cndmask_b32_e64 v45, v45, v12, vcc
	v_cndmask_b32_e64 v58, v58, v13, vcc
	v_add_u32_e32 v13, 2, v31
	v_cmp_gt_u32_e64 s[18:19], v32, v13
	v_add_u32_e32 v13, 3, v31
	s_nop 0
	v_cndmask_b32_e64 v12, -1.0, v11, s[18:19]
	v_cmp_gt_f32_e64 vcc, v12, v33
	s_nop 1
	v_cndmask_b32_e64 v14, v12, v33, vcc
	v_cmp_gt_f32_e64 s[14:15], v14, v34
	v_cndmask_b32_e64 v33, v33, v12, vcc
	v_cndmask_b32_e64 v15, v13, v46, vcc
	v_cndmask_b32_e64 v46, v46, v13, vcc
	v_cndmask_b32_e64 v12, v14, v34, s[14:15]
	v_cmp_gt_f32_e64 vcc, v12, v35
	v_cndmask_b32_e64 v34, v34, v14, s[14:15]
	v_cndmask_b32_e64 v13, v15, v47, s[14:15]
	v_cndmask_b32_e64 v47, v47, v15, s[14:15]
	v_cndmask_b32_e64 v14, v12, v35, vcc
	v_cmp_gt_f32_e64 s[14:15], v14, v36
	v_cndmask_b32_e64 v35, v35, v12, vcc
	v_cndmask_b32_e64 v15, v13, v48, vcc
	v_cndmask_b32_e64 v48, v48, v13, vcc
	v_cndmask_b32_e64 v12, v14, v36, s[14:15]
	v_cmp_gt_f32_e64 vcc, v12, v37
	v_cndmask_b32_e64 v36, v36, v14, s[14:15]
	v_cndmask_b32_e64 v13, v15, v49, s[14:15]
	v_cndmask_b32_e64 v49, v49, v15, s[14:15]
	v_cndmask_b32_e64 v14, v12, v37, vcc
	v_cmp_gt_f32_e64 s[14:15], v14, v38
	v_cndmask_b32_e64 v37, v37, v12, vcc
	v_cndmask_b32_e64 v15, v13, v50, vcc
	v_cndmask_b32_e64 v50, v50, v13, vcc
	v_cndmask_b32_e64 v12, v14, v38, s[14:15]
	v_cmp_gt_f32_e64 vcc, v12, v39
	v_cndmask_b32_e64 v38, v38, v14, s[14:15]
	v_cndmask_b32_e64 v13, v15, v51, s[14:15]
	v_cndmask_b32_e64 v51, v51, v15, s[14:15]
	v_cndmask_b32_e64 v14, v12, v39, vcc
	v_cmp_gt_f32_e64 s[14:15], v14, v40
	v_cndmask_b32_e64 v39, v39, v12, vcc
	v_cndmask_b32_e64 v15, v13, v52, vcc
	v_cndmask_b32_e64 v52, v52, v13, vcc
	v_cndmask_b32_e64 v12, v14, v40, s[14:15]
	v_cmp_gt_f32_e64 vcc, v12, v41
	v_cndmask_b32_e64 v40, v40, v14, s[14:15]
	v_cndmask_b32_e64 v13, v15, v53, s[14:15]
	v_cndmask_b32_e64 v53, v53, v15, s[14:15]
	v_cndmask_b32_e64 v14, v12, v41, vcc
	v_cmp_gt_f32_e64 s[14:15], v14, v42
	v_cndmask_b32_e64 v41, v41, v12, vcc
	v_cndmask_b32_e64 v15, v13, v54, vcc
	v_cndmask_b32_e64 v54, v54, v13, vcc
	v_cndmask_b32_e64 v12, v14, v42, s[14:15]
	v_cmp_gt_f32_e64 vcc, v12, v43
	v_cndmask_b32_e64 v42, v42, v14, s[14:15]
	v_cndmask_b32_e64 v13, v15, v55, s[14:15]
	v_cndmask_b32_e64 v55, v55, v15, s[14:15]
	v_cndmask_b32_e64 v14, v12, v43, vcc
	v_cmp_gt_f32_e64 s[14:15], v14, v44
	v_cndmask_b32_e64 v43, v43, v12, vcc
	v_cndmask_b32_e64 v15, v13, v56, vcc
	v_cndmask_b32_e64 v56, v56, v13, vcc
	v_cndmask_b32_e64 v12, v14, v44, s[14:15]
	v_cmp_gt_f32_e64 vcc, v12, v45
	v_cndmask_b32_e64 v44, v44, v14, s[14:15]
	v_cndmask_b32_e64 v13, v15, v57, s[14:15]
	v_cndmask_b32_e64 v57, v57, v15, s[14:15]
	v_cndmask_b32_e64 v14, v12, v45, vcc
	s_nop 0
	v_cndmask_b32_e64 v45, v45, v12, vcc
	v_cndmask_b32_e64 v58, v58, v13, vcc
	v_add_u32_e32 v31, 4, v31
	s_add_i32 s26, s26, 1
	s_cmp_lt_u32 s26, s24
	s_cbranch_scc1 .Ltopk_loop
; DI void nsa_item(const Params& p, int bk, int qb, char* smem, float Mb) {
;     ...
;             if (ncand > need) {
;                 float key[4][4];
; #pragma unroll
;                 for (int u = 0; u < 4; ++u)
; #pragma unroll
;                     for (int r = 0; r < 4; ++r) {
;                         const int j = lane + 64 * r;
;                         key[u][r] = (j >= 1 && j <= cur - 2) ? imp[(qi + u) * 260 + j] : -1.f;
;                     }
;                 for (int s = 0; s < need; ++s) {
; #pragma unroll
;                     for (int u = 0; u < 4; ++u) {
;                         const float best = wave_max(fmaxf(fmaxf(key[u][0], key[u][1]), fmaxf(key[u][2], key[u][3])));
;                         int jstar = 1 << 20;
; #pragma unroll
;                         for (int r = 3; r >= 0; --r) {
;                             const unsigned long long bm = __ballot(key[u][r] == best);
;                             if (bm) jstar = 64 * r + (int)__builtin_ctzll(bm);
;                         }
; #pragma unroll
;                         for (int r = 0; r < 4; ++r) if (lane + 64 * r == jstar) key[u][r] = -1.f;
;                         if (lane == 0) sel[(qi + u) * 16 + nforced + s] = jstar;
;                     }
;                 }
	v_mul_u32_u24_e32 v10, 104, v146
	v_add_u32_e32 v10, s90, v10
	ds_write2_b32 v10, v33, v46 offset0:0 offset1:1
	ds_write2_b32 v10, v34, v47 offset0:2 offset1:3
	ds_write2_b32 v10, v35, v48 offset0:4 offset1:5
	ds_write2_b32 v10, v36, v49 offset0:6 offset1:7
	ds_write2_b32 v10, v37, v50 offset0:8 offset1:9
	ds_write2_b32 v10, v38, v51 offset0:10 offset1:11
	ds_write2_b32 v10, v39, v52 offset0:12 offset1:13
	ds_write2_b32 v10, v40, v53 offset0:14 offset1:15
	ds_write2_b32 v10, v41, v54 offset0:16 offset1:17
	ds_write2_b32 v10, v42, v55 offset0:18 offset1:19
	ds_write2_b32 v10, v43, v56 offset0:20 offset1:21
	ds_write2_b32 v10, v44, v57 offset0:22 offset1:23
	ds_write2_b32 v10, v45, v58 offset0:24 offset1:25
	v_xor_b32_e32 v9, 16, v146
	v_mul_u32_u24_e32 v9, 104, v9
	v_add_u32_e32 v9, s90, v9
	s_waitcnt lgkmcnt(0)
	s_mov_b32 s26, 0
